# baseline (speedup 1.0000x reference)
; #define PG8_STAGE(bufoff, gbase, voff) do { _Pragma("unroll") for (int _i = 0; _i < 2; ++_i) \
;         __builtin_amdgcn_global_load_lds((const unsigned*)((const char*)(gbase) + (voff)[_i]), (LAS unsigned*)(lds + (bufoff) + ldsw + _i * 8192), 16, 0, 0); } while (0)
; #define PG8_LDA(dst, b, h) do { _Pragma("unroll") for (int m = 0; m < 4; ++m) _Pragma("unroll") for (int k = 0; k < 2; ++k) dst[m][k] = *(const LAS bf16x8*)(lds + PG8_SA(b, h) + aoff + m * 2048 + k * 1024); } while (0)
; #define PG8_LDB(dst, b, h) do { _Pragma("unroll") for (int n = 0; n < 2; ++n) _Pragma("unroll") for (int k = 0; k < 2; ++k) dst[n][k] = *(const LAS bf16x8*)(lds + PG8_SB(b, h) + boff + n * 2048 + k * 1024); } while (0)
; #define PG8_WAIT_V(n) asm volatile("s_waitcnt vmcnt(" #n ")" ::: "memory")
; #define PG8_WAIT_L(n) asm volatile("s_waitcnt lgkmcnt(" #n ")" ::: "memory")
; #define PG8_BAR __builtin_amdgcn_s_barrier()
; #define PG8_SCHED __builtin_amdgcn_sched_barrier(0)
; template <class Epi, class Sched, bool FUSED = false, bool APERM = false>
; __device__ __forceinline__ void gemm_phase(int wid_s, LAS unsigned char* lds, const Gemm g, const Sched& S, const Epi& E) {
;     ...
;             const bool last = (t == nt - 2);
;             const char* a1 = cA + (size_t)(t + 1) * kstep;
;             const char* a2 = last ? nA : cA + (size_t)(t + 2) * kstep; const char* b2 = last ? nB : cB + (size_t)(t + 2) * kstep;
;             const char* a3 = a2 + kstep; const char* b3 = b2 + kstep;
;             if (last && has_next) S.a_ready(nxt);
;             PG8_LDB(B0, 0, 0); PG8_LDB(B1, 0, 1); PG8_SCHED; PG8_LDA(At, 0, 0); PG8_STAGE(PG8_SA(1, 1), a1 + hstep, voffA);
;             PG8_WAIT_V(8); PG8_WAIT_L(0); PG8_BAR; PG8_MMA(0, 0, At, B0); PG8_MMA(0, 1, At, B1); PG8_BAR; PG8_SCHED;
;             PG8_LDA(At, 0, 1); PG8_STAGE(PG8_SB(0, 0), b2, voffB); PG8_STAGE(PG8_SB(0, 1), b2 + hstep, voffB); PG8_STAGE(PG8_SA(0, 0), a2, voffA);
;             PG8_WAIT_V(8); PG8_WAIT_L(0); PG8_BAR; PG8_MMA(1, 0, At, B0); PG8_MMA(1, 1, At, B1); PG8_BAR; PG8_SCHED;
.LBB0_342:
	s_add_u32 s38, s36, 0xfff80080
	s_addc_u32 s39, s37, -1
	s_add_i32 s64, 0, 0x10000
	s_cmp_eq_u32 s63, 28
	s_cselect_b32 s41, s1, s39
	s_cselect_b32 s40, s23, s38
	s_cselect_b32 s39, s25, s62
	s_cselect_b32 s38, s35, s61
	s_add_i32 s66, 0, 0x14000
	v_add_u32_e32 v144, s64, v227
	v_add_u32_e32 v160, s66, v227
	ds_read_b128 v[132:135], v144
	ds_read_b128 v[136:139], v144 offset:1024
	ds_read_b128 v[140:143], v144 offset:2048
	ds_read_b128 v[144:147], v144 offset:3072
	ds_read_b128 v[148:151], v160
	ds_read_b128 v[152:155], v160 offset:1024
	ds_read_b128 v[156:159], v160 offset:2048
	ds_read_b128 v[160:163], v160 offset:3072
	v_lshl_add_u64 v[214:215], s[36:37], 0, v[212:213]
	s_add_i32 m0, s48, 0xc000
	ds_read_b128 v[164:167], v228
	ds_read_b128 v[168:171], v228 offset:1024
	ds_read_b128 v[172:175], v228 offset:2048
	ds_read_b128 v[176:179], v228 offset:3072
	ds_read_b128 v[180:183], v228 offset:4096
	ds_read_b128 v[184:187], v228 offset:5120
	ds_read_b128 v[188:191], v228 offset:6144
	ds_read_b128 v[192:195], v228 offset:7168
	global_load_lds_dwordx4 v[214:215], off
	v_lshl_add_u64 v[214:215], s[36:37], 0, v[210:211]
	s_add_i32 m0, s48, 0xe000
	s_nop 0
	global_load_lds_dwordx4 v[214:215], off
	s_waitcnt vmcnt(8)
	s_waitcnt lgkmcnt(0)
	v_mfma_f32_16x16x32_f16 v[128:131], v[132:135], v[164:167], v[128:131]
	v_mfma_f32_16x16x32_f16 v[124:127], v[140:143], v[164:167], v[124:127]
	v_mfma_f32_16x16x32_f16 v[112:115], v[132:135], v[172:175], v[112:115]
	v_mfma_f32_16x16x32_f16 v[108:111], v[140:143], v[172:175], v[108:111]
	v_mfma_f32_16x16x32_f16 v[96:99], v[132:135], v[180:183], v[96:99]
	v_mfma_f32_16x16x32_f16 v[92:95], v[140:143], v[180:183], v[92:95]
	v_mfma_f32_16x16x32_f16 v[80:83], v[132:135], v[188:191], v[80:83]
	v_mfma_f32_16x16x32_f16 v[76:79], v[140:143], v[188:191], v[76:79]
	s_barrier
	s_setprio 1
	v_mfma_f32_16x16x32_f16 v[128:131], v[136:139], v[168:171], v[128:131]
	v_mfma_f32_16x16x32_f16 v[124:127], v[144:147], v[168:171], v[124:127]
	v_mfma_f32_16x16x32_f16 v[112:115], v[136:139], v[176:179], v[112:115]
	v_mfma_f32_16x16x32_f16 v[108:111], v[144:147], v[176:179], v[108:111]
	v_mfma_f32_16x16x32_f16 v[96:99], v[136:139], v[184:187], v[96:99]
	v_mfma_f32_16x16x32_f16 v[92:95], v[144:147], v[184:187], v[92:95]
	v_mfma_f32_16x16x32_f16 v[80:83], v[136:139], v[192:195], v[80:83]
	v_mfma_f32_16x16x32_f16 v[76:79], v[144:147], v[192:195], v[76:79]
	v_mfma_f32_16x16x32_f16 v[120:123], v[148:151], v[164:167], v[120:123]
	v_mfma_f32_16x16x32_f16 v[116:119], v[156:159], v[164:167], v[116:119]
	v_mfma_f32_16x16x32_f16 v[104:107], v[148:151], v[172:175], v[104:107]
	v_mfma_f32_16x16x32_f16 v[100:103], v[156:159], v[172:175], v[100:103]
	v_mfma_f32_16x16x32_f16 v[88:91], v[148:151], v[180:183], v[88:91]
	v_mfma_f32_16x16x32_f16 v[84:87], v[156:159], v[180:183], v[84:87]
	v_mfma_f32_16x16x32_f16 v[68:71], v[148:151], v[188:191], v[68:71]
	v_mfma_f32_16x16x32_f16 v[72:75], v[156:159], v[188:191], v[72:75]
	v_mfma_f32_16x16x32_f16 v[120:123], v[152:155], v[168:171], v[120:123]
	v_mfma_f32_16x16x32_f16 v[116:119], v[160:163], v[168:171], v[116:119]
	v_mfma_f32_16x16x32_f16 v[104:107], v[152:155], v[176:179], v[104:107]
	v_mfma_f32_16x16x32_f16 v[100:103], v[160:163], v[176:179], v[100:103]
	v_mfma_f32_16x16x32_f16 v[88:91], v[152:155], v[184:187], v[88:91]
	v_mfma_f32_16x16x32_f16 v[84:87], v[160:163], v[184:187], v[84:87]
	v_mfma_f32_16x16x32_f16 v[68:71], v[152:155], v[192:195], v[68:71]
	v_mfma_f32_16x16x32_f16 v[72:75], v[160:163], v[192:195], v[72:75]
	s_setprio 0
	s_barrier
	s_add_i32 s64, s64, s47
	v_lshl_add_u64 v[214:215], s[38:39], 0, v[0:1]
	s_mov_b32 m0, s64
	ds_read_b128 v[164:167], v228 offset:16384
	ds_read_b128 v[168:171], v228 offset:17408
	ds_read_b128 v[172:175], v228 offset:18432
	ds_read_b128 v[176:179], v228 offset:19456
	ds_read_b128 v[180:183], v228 offset:20480
	ds_read_b128 v[184:187], v228 offset:21504
	ds_read_b128 v[188:191], v228 offset:22528
	ds_read_b128 v[192:195], v228 offset:23552
	global_load_lds_dwordx4 v[214:215], off
	s_add_i32 m0, s64, 0x2000
	s_add_u32 s64, s38, 0x80000
	v_lshl_add_u64 v[216:217], s[38:39], 0, v[208:209]
	s_addc_u32 s65, s39, 0
	s_add_i32 s66, s66, s47
	global_load_lds_dwordx4 v[216:217], off
	v_lshl_add_u64 v[218:219], s[64:65], 0, v[0:1]
	s_mov_b32 m0, s66
	v_lshl_add_u64 v[220:221], s[40:41], 0, v[208:209]
	global_load_lds_dwordx4 v[218:219], off
	v_lshl_add_u64 v[218:219], s[64:65], 0, v[208:209]
	s_add_i32 m0, s66, 0x2000
	s_nop 0
	global_load_lds_dwordx4 v[218:219], off
	v_lshl_add_u64 v[218:219], s[40:41], 0, v[0:1]
	s_mov_b32 m0, s48
	s_nop 0
	global_load_lds_dwordx4 v[218:219], off
	s_mov_b32 m0, s49
	s_nop 0
	global_load_lds_dwordx4 v[220:221], off
	s_waitcnt vmcnt(8)
	s_waitcnt lgkmcnt(0)
	v_mfma_f32_16x16x32_f16 v[64:67], v[132:135], v[164:167], v[64:67]
	v_mfma_f32_16x16x32_f16 v[60:63], v[140:143], v[164:167], v[60:63]
	v_mfma_f32_16x16x32_f16 v[48:51], v[132:135], v[172:175], v[48:51]
	v_mfma_f32_16x16x32_f16 v[44:47], v[140:143], v[172:175], v[44:47]
	v_mfma_f32_16x16x32_f16 v[32:35], v[132:135], v[180:183], v[32:35]
	v_mfma_f32_16x16x32_f16 v[28:31], v[140:143], v[180:183], v[28:31]
	v_mfma_f32_16x16x32_f16 v[12:15], v[132:135], v[188:191], v[12:15]
	v_mfma_f32_16x16x32_f16 v[16:19], v[140:143], v[188:191], v[16:19]
	s_barrier
; #define PG8_STAGE(bufoff, gbase, voff) do { _Pragma("unroll") for (int _i = 0; _i < 2; ++_i) \
;         __builtin_amdgcn_global_load_lds((const unsigned*)((const char*)(gbase) + (voff)[_i]), (LAS unsigned*)(lds + (bufoff) + ldsw + _i * 8192), 16, 0, 0); } while (0)
; #define PG8_LDA(dst, b, h) do { _Pragma("unroll") for (int m = 0; m < 4; ++m) _Pragma("unroll") for (int k = 0; k < 2; ++k) dst[m][k] = *(const LAS bf16x8*)(lds + PG8_SA(b, h) + aoff + m * 2048 + k * 1024); } while (0)
; #define PG8_LDB(dst, b, h) do { _Pragma("unroll") for (int n = 0; n < 2; ++n) _Pragma("unroll") for (int k = 0; k < 2; ++k) dst[n][k] = *(const LAS bf16x8*)(lds + PG8_SB(b, h) + boff + n * 2048 + k * 1024); } while (0)
; #define PG8_WAIT_V(n) asm volatile("s_waitcnt vmcnt(" #n ")" ::: "memory")
; #define PG8_WAIT_L(n) asm volatile("s_waitcnt lgkmcnt(" #n ")" ::: "memory")
; #define PG8_BAR __builtin_amdgcn_s_barrier()
; #define PG8_SCHED __builtin_amdgcn_sched_barrier(0)
; template <class Epi, class Sched, bool FUSED = false, bool APERM = false>
; __device__ __forceinline__ void gemm_phase(int wid_s, LAS unsigned char* lds, const Gemm g, const Sched& S, const Epi& E) {
;     ...
;             PG8_WAIT_V(8); PG8_WAIT_L(0); PG8_BAR; PG8_MMA(1, 0, At, B0); PG8_MMA(1, 1, At, B1); PG8_BAR; PG8_SCHED;
;             PG8_LDB(B0, 1, 0); PG8_LDB(B1, 1, 1); PG8_SCHED; PG8_LDA(At, 1, 0); PG8_STAGE(PG8_SA(0, 1), a2 + hstep, voffA);
;             PG8_WAIT_V(8); PG8_WAIT_L(0); PG8_BAR; PG8_MMA(0, 0, At, B0); PG8_MMA(0, 1, At, B1); PG8_BAR; PG8_SCHED;
	s_setprio 1
	v_mfma_f32_16x16x32_f16 v[64:67], v[136:139], v[168:171], v[64:67]
	v_mfma_f32_16x16x32_f16 v[60:63], v[144:147], v[168:171], v[60:63]
	v_mfma_f32_16x16x32_f16 v[48:51], v[136:139], v[176:179], v[48:51]
	v_mfma_f32_16x16x32_f16 v[44:47], v[144:147], v[176:179], v[44:47]
	v_mfma_f32_16x16x32_f16 v[32:35], v[136:139], v[184:187], v[32:35]
	v_mfma_f32_16x16x32_f16 v[28:31], v[144:147], v[184:187], v[28:31]
	v_mfma_f32_16x16x32_f16 v[12:15], v[136:139], v[192:195], v[12:15]
	v_mfma_f32_16x16x32_f16 v[16:19], v[144:147], v[192:195], v[16:19]
	v_mfma_f32_16x16x32_f16 v[56:59], v[148:151], v[164:167], v[56:59]
	v_mfma_f32_16x16x32_f16 v[52:55], v[156:159], v[164:167], v[52:55]
	v_mfma_f32_16x16x32_f16 v[40:43], v[148:151], v[172:175], v[40:43]
	v_mfma_f32_16x16x32_f16 v[36:39], v[156:159], v[172:175], v[36:39]
	v_mfma_f32_16x16x32_f16 v[24:27], v[148:151], v[180:183], v[24:27]
	v_mfma_f32_16x16x32_f16 v[20:23], v[156:159], v[180:183], v[20:23]
	v_mfma_f32_16x16x32_f16 v[4:7], v[148:151], v[188:191], v[4:7]
	v_mfma_f32_16x16x32_f16 v[8:11], v[156:159], v[188:191], v[8:11]
	v_mfma_f32_16x16x32_f16 v[56:59], v[152:155], v[168:171], v[56:59]
	v_mfma_f32_16x16x32_f16 v[52:55], v[160:163], v[168:171], v[52:55]
	v_mfma_f32_16x16x32_f16 v[40:43], v[152:155], v[176:179], v[40:43]
	v_mfma_f32_16x16x32_f16 v[36:39], v[160:163], v[176:179], v[36:39]
	v_mfma_f32_16x16x32_f16 v[24:27], v[152:155], v[184:187], v[24:27]
	v_mfma_f32_16x16x32_f16 v[20:23], v[160:163], v[184:187], v[20:23]
	v_mfma_f32_16x16x32_f16 v[4:7], v[152:155], v[192:195], v[4:7]
	v_mfma_f32_16x16x32_f16 v[8:11], v[160:163], v[192:195], v[8:11]
	s_setprio 0
	s_barrier
	s_add_i32 s64, 0, 0x18000
	s_add_i32 s65, 0, 0x1c000
	v_add_u32_e32 v144, s64, v227
	v_add_u32_e32 v160, s65, v227
	ds_read_b128 v[132:135], v144
	ds_read_b128 v[136:139], v144 offset:1024
	ds_read_b128 v[140:143], v144 offset:2048
	ds_read_b128 v[144:147], v144 offset:3072
	ds_read_b128 v[148:151], v160
	ds_read_b128 v[152:155], v160 offset:1024
	ds_read_b128 v[156:159], v160 offset:2048
	ds_read_b128 v[160:163], v160 offset:3072
	s_add_u32 s40, s40, 0x80000
	s_addc_u32 s41, s41, 0
	s_mov_b32 m0, s50
	v_lshl_add_u64 v[222:223], s[40:41], 0, v[0:1]
	ds_read_b128 v[164:167], v228 offset:32768
	ds_read_b128 v[168:171], v228 offset:33792
	ds_read_b128 v[172:175], v228 offset:34816
	ds_read_b128 v[176:179], v228 offset:35840
	ds_read_b128 v[180:183], v228 offset:36864
	ds_read_b128 v[184:187], v228 offset:37888
	ds_read_b128 v[188:191], v228 offset:38912
	ds_read_b128 v[192:195], v228 offset:39936
	global_load_lds_dwordx4 v[222:223], off
	v_lshl_add_u64 v[222:223], s[40:41], 0, v[208:209]
	s_mov_b32 m0, s51
	s_nop 0
	global_load_lds_dwordx4 v[222:223], off
	s_waitcnt vmcnt(8)
	s_waitcnt lgkmcnt(0)
	v_mfma_f32_16x16x32_f16 v[128:131], v[132:135], v[164:167], v[128:131]
	v_mfma_f32_16x16x32_f16 v[124:127], v[140:143], v[164:167], v[124:127]
	v_mfma_f32_16x16x32_f16 v[112:115], v[132:135], v[172:175], v[112:115]
	v_mfma_f32_16x16x32_f16 v[108:111], v[140:143], v[172:175], v[108:111]
	v_mfma_f32_16x16x32_f16 v[96:99], v[132:135], v[180:183], v[96:99]
	v_mfma_f32_16x16x32_f16 v[92:95], v[140:143], v[180:183], v[92:95]
	v_mfma_f32_16x16x32_f16 v[80:83], v[132:135], v[188:191], v[80:83]
	v_mfma_f32_16x16x32_f16 v[76:79], v[140:143], v[188:191], v[76:79]
	s_barrier
	s_setprio 1
	v_mfma_f32_16x16x32_f16 v[128:131], v[136:139], v[168:171], v[128:131]
	v_mfma_f32_16x16x32_f16 v[124:127], v[144:147], v[168:171], v[124:127]
	v_mfma_f32_16x16x32_f16 v[112:115], v[136:139], v[176:179], v[112:115]
	v_mfma_f32_16x16x32_f16 v[108:111], v[144:147], v[176:179], v[108:111]
	v_mfma_f32_16x16x32_f16 v[96:99], v[136:139], v[184:187], v[96:99]
	v_mfma_f32_16x16x32_f16 v[92:95], v[144:147], v[184:187], v[92:95]
	v_mfma_f32_16x16x32_f16 v[80:83], v[136:139], v[192:195], v[80:83]
	v_mfma_f32_16x16x32_f16 v[76:79], v[144:147], v[192:195], v[76:79]
	v_mfma_f32_16x16x32_f16 v[120:123], v[148:151], v[164:167], v[120:123]
	v_mfma_f32_16x16x32_f16 v[116:119], v[156:159], v[164:167], v[116:119]
	v_mfma_f32_16x16x32_f16 v[104:107], v[148:151], v[172:175], v[104:107]
	v_mfma_f32_16x16x32_f16 v[100:103], v[156:159], v[172:175], v[100:103]
	v_mfma_f32_16x16x32_f16 v[88:91], v[148:151], v[180:183], v[88:91]
	v_mfma_f32_16x16x32_f16 v[84:87], v[156:159], v[180:183], v[84:87]
	v_mfma_f32_16x16x32_f16 v[68:71], v[148:151], v[188:191], v[68:71]
	v_mfma_f32_16x16x32_f16 v[72:75], v[156:159], v[188:191], v[72:75]
	v_mfma_f32_16x16x32_f16 v[120:123], v[152:155], v[168:171], v[120:123]
	v_mfma_f32_16x16x32_f16 v[116:119], v[160:163], v[168:171], v[116:119]
	v_mfma_f32_16x16x32_f16 v[104:107], v[152:155], v[176:179], v[104:107]
	v_mfma_f32_16x16x32_f16 v[100:103], v[160:163], v[176:179], v[100:103]
	v_mfma_f32_16x16x32_f16 v[88:91], v[152:155], v[184:187], v[88:91]
	v_mfma_f32_16x16x32_f16 v[84:87], v[160:163], v[184:187], v[84:87]
	v_mfma_f32_16x16x32_f16 v[68:71], v[152:155], v[192:195], v[68:71]
	v_mfma_f32_16x16x32_f16 v[72:75], v[160:163], v[192:195], v[72:75]
	s_setprio 0
	s_barrier
; #define PG8_STAGE(bufoff, gbase, voff) do { _Pragma("unroll") for (int _i = 0; _i < 2; ++_i) \
;         __builtin_amdgcn_global_load_lds((const unsigned*)((const char*)(gbase) + (voff)[_i]), (LAS unsigned*)(lds + (bufoff) + ldsw + _i * 8192), 16, 0, 0); } while (0)
; #define PG8_LDA(dst, b, h) do { _Pragma("unroll") for (int m = 0; m < 4; ++m) _Pragma("unroll") for (int k = 0; k < 2; ++k) dst[m][k] = *(const LAS bf16x8*)(lds + PG8_SA(b, h) + aoff + m * 2048 + k * 1024); } while (0)
; #define PG8_WAIT_V(n) asm volatile("s_waitcnt vmcnt(" #n ")" ::: "memory")
; #define PG8_WAIT_L(n) asm volatile("s_waitcnt lgkmcnt(" #n ")" ::: "memory")
; #define PG8_BAR __builtin_amdgcn_s_barrier()
; #define PG8_SCHED __builtin_amdgcn_sched_barrier(0)
; template <class Epi, class Sched, bool FUSED = false, bool APERM = false>
; __device__ __forceinline__ void gemm_phase(int wid_s, LAS unsigned char* lds, const Gemm g, const Sched& S, const Epi& E) {
;     ...
;             PG8_LDA(At, 1, 1); PG8_STAGE(PG8_SB(1, 0), b3, voffB); PG8_STAGE(PG8_SB(1, 1), b3 + hstep, voffB); PG8_STAGE(PG8_SA(1, 0), a3, voffA);
;             PG8_WAIT_V(8); PG8_WAIT_L(0); PG8_BAR; PG8_MMA(1, 0, At, B0); PG8_MMA(1, 1, At, B1); PG8_BAR; PG8_SCHED;
;         }
;         if (wr == 0) PG8_BAR;
	s_add_i32 s40, s64, s47
	v_lshl_add_u64 v[214:215], v[214:215], 0, s[12:13]
	s_mov_b32 m0, s40
	ds_read_b128 v[164:167], v228 offset:49152
	ds_read_b128 v[168:171], v228 offset:50176
	ds_read_b128 v[172:175], v228 offset:51200
	ds_read_b128 v[176:179], v228 offset:52224
	ds_read_b128 v[180:183], v228 offset:53248
	ds_read_b128 v[184:187], v228 offset:54272
	ds_read_b128 v[188:191], v228 offset:55296
	ds_read_b128 v[192:195], v228 offset:56320
	global_load_lds_dwordx4 v[214:215], off
	s_add_i32 m0, s40, 0x2000
	s_add_u32 s38, s38, 0x80080
	v_lshl_add_u64 v[214:215], v[216:217], 0, s[12:13]
	s_addc_u32 s39, s39, 0
	s_add_i32 s40, s65, s47
	global_load_lds_dwordx4 v[214:215], off
	v_lshl_add_u64 v[214:215], s[38:39], 0, v[0:1]
	s_mov_b32 m0, s40
	s_nop 0
	global_load_lds_dwordx4 v[214:215], off
	v_lshl_add_u64 v[214:215], s[38:39], 0, v[208:209]
	s_add_i32 m0, s40, 0x2000
	s_nop 0
	global_load_lds_dwordx4 v[214:215], off
	v_lshl_add_u64 v[214:215], v[218:219], 0, s[12:13]
	s_mov_b32 m0, s55
	s_nop 0
	global_load_lds_dwordx4 v[214:215], off
	v_lshl_add_u64 v[214:215], v[220:221], 0, s[12:13]
	s_mov_b32 m0, s56
	s_nop 0
	global_load_lds_dwordx4 v[214:215], off
	s_waitcnt vmcnt(8)
	s_waitcnt lgkmcnt(0)
	v_mfma_f32_16x16x32_f16 v[64:67], v[132:135], v[164:167], v[64:67]
	v_mfma_f32_16x16x32_f16 v[60:63], v[140:143], v[164:167], v[60:63]
	v_mfma_f32_16x16x32_f16 v[48:51], v[132:135], v[172:175], v[48:51]
	v_mfma_f32_16x16x32_f16 v[44:47], v[140:143], v[172:175], v[44:47]
	v_mfma_f32_16x16x32_f16 v[32:35], v[132:135], v[180:183], v[32:35]
	v_mfma_f32_16x16x32_f16 v[28:31], v[140:143], v[180:183], v[28:31]
	v_mfma_f32_16x16x32_f16 v[12:15], v[132:135], v[188:191], v[12:15]
	v_mfma_f32_16x16x32_f16 v[16:19], v[140:143], v[188:191], v[16:19]
	s_barrier
	s_setprio 1
	v_mfma_f32_16x16x32_f16 v[64:67], v[136:139], v[168:171], v[64:67]
	v_mfma_f32_16x16x32_f16 v[60:63], v[144:147], v[168:171], v[60:63]
	v_mfma_f32_16x16x32_f16 v[48:51], v[136:139], v[176:179], v[48:51]
	v_mfma_f32_16x16x32_f16 v[44:47], v[144:147], v[176:179], v[44:47]
	v_mfma_f32_16x16x32_f16 v[32:35], v[136:139], v[184:187], v[32:35]
	v_mfma_f32_16x16x32_f16 v[28:31], v[144:147], v[184:187], v[28:31]
	v_mfma_f32_16x16x32_f16 v[12:15], v[136:139], v[192:195], v[12:15]
	v_mfma_f32_16x16x32_f16 v[16:19], v[144:147], v[192:195], v[16:19]
	v_mfma_f32_16x16x32_f16 v[56:59], v[148:151], v[164:167], v[56:59]
	v_mfma_f32_16x16x32_f16 v[52:55], v[156:159], v[164:167], v[52:55]
	v_mfma_f32_16x16x32_f16 v[40:43], v[148:151], v[172:175], v[40:43]
	v_mfma_f32_16x16x32_f16 v[36:39], v[156:159], v[172:175], v[36:39]
	v_mfma_f32_16x16x32_f16 v[24:27], v[148:151], v[180:183], v[24:27]
	v_mfma_f32_16x16x32_f16 v[20:23], v[156:159], v[180:183], v[20:23]
	v_mfma_f32_16x16x32_f16 v[4:7], v[148:151], v[188:191], v[4:7]
	v_mfma_f32_16x16x32_f16 v[8:11], v[156:159], v[188:191], v[8:11]
	v_mfma_f32_16x16x32_f16 v[56:59], v[152:155], v[168:171], v[56:59]
	v_mfma_f32_16x16x32_f16 v[52:55], v[160:163], v[168:171], v[52:55]
	v_mfma_f32_16x16x32_f16 v[40:43], v[152:155], v[176:179], v[40:43]
	v_mfma_f32_16x16x32_f16 v[36:39], v[160:163], v[176:179], v[36:39]
	v_mfma_f32_16x16x32_f16 v[24:27], v[152:155], v[184:187], v[24:27]
	v_mfma_f32_16x16x32_f16 v[20:23], v[160:163], v[184:187], v[20:23]
	v_mfma_f32_16x16x32_f16 v[4:7], v[152:155], v[192:195], v[4:7]
	v_mfma_f32_16x16x32_f16 v[8:11], v[160:163], v[192:195], v[8:11]
	s_setprio 0
	s_barrier
	s_add_i32 s63, s63, 2
	s_add_u32 s61, s61, 0x100
	s_addc_u32 s62, s62, 0
	s_add_u32 s36, s36, 0x100
	s_addc_u32 s37, s37, 0
	s_cmp_gt_u32 s63, 29
	s_cbranch_scc0 .LBB0_342
	s_and_b64 vcc, exec, s[14:15]
	s_cbranch_vccz .LBB0_345
	s_barrier

; #define PG8_STAGE(bufoff, gbase, voff) do { _Pragma("unroll") for (int _i = 0; _i < 2; ++_i) \
;         __builtin_amdgcn_global_load_lds((const unsigned*)((const char*)(gbase) + (voff)[_i]), (LAS unsigned*)(lds + (bufoff) + ldsw + _i * 8192), 16, 0, 0); } while (0)
; #define PG8_LDA(dst, b, h) do { _Pragma("unroll") for (int m = 0; m < 4; ++m) _Pragma("unroll") for (int k = 0; k < 2; ++k) dst[m][k] = *(const LAS bf16x8*)(lds + PG8_SA(b, h) + aoff + m * 2048 + k * 1024); } while (0)
; #define PG8_LDB(dst, b, h) do { _Pragma("unroll") for (int n = 0; n < 2; ++n) _Pragma("unroll") for (int k = 0; k < 2; ++k) dst[n][k] = *(const LAS bf16x8*)(lds + PG8_SB(b, h) + boff + n * 2048 + k * 1024); } while (0)
; #define PG8_WAIT_V(n) asm volatile("s_waitcnt vmcnt(" #n ")" ::: "memory")
; #define PG8_WAIT_L(n) asm volatile("s_waitcnt lgkmcnt(" #n ")" ::: "memory")
; #define PG8_BAR __builtin_amdgcn_s_barrier()
; #define PG8_SCHED __builtin_amdgcn_sched_barrier(0)
; template <class Epi, class Sched, bool FUSED = false, bool APERM = false>
; __device__ __forceinline__ void gemm_phase(int wid_s, LAS unsigned char* lds, const Gemm g, const Sched& S, const Epi& E) {
;     ...
;             const bool last = (t == nt - 2);
;             const char* a1 = cA + (size_t)(t + 1) * kstep;
;             const char* a2 = last ? nA : cA + (size_t)(t + 2) * kstep; const char* b2 = last ? nB : cB + (size_t)(t + 2) * kstep;
;             const char* a3 = a2 + kstep; const char* b3 = b2 + kstep;
;             if (last && has_next) S.a_ready(nxt);
;             PG8_LDB(B0, 0, 0); PG8_LDB(B1, 0, 1); PG8_SCHED; PG8_LDA(At, 0, 0); PG8_STAGE(PG8_SA(1, 1), a1 + hstep, voffA);
;             PG8_WAIT_V(8); PG8_WAIT_L(0); PG8_BAR; PG8_MMA(0, 0, At, B0); PG8_MMA(0, 1, At, B1); PG8_BAR; PG8_SCHED;
;             PG8_LDA(At, 0, 1); PG8_STAGE(PG8_SB(0, 0), b2, voffB); PG8_STAGE(PG8_SB(0, 1), b2 + hstep, voffB); PG8_STAGE(PG8_SA(0, 0), a2, voffA);
;             PG8_WAIT_V(8); PG8_WAIT_L(0); PG8_BAR; PG8_MMA(1, 0, At, B0); PG8_MMA(1, 1, At, B1); PG8_BAR; PG8_SCHED;
.LBB0_582:
	s_add_u32 s24, s22, 0xfffe0080
	s_addc_u32 s25, s23, -1
	s_add_i32 s50, 0, 0x10000
	s_cmp_eq_u32 s49, 4
	s_cselect_b32 s27, s15, s25
	s_cselect_b32 s26, s45, s24
	v_add_u32_e32 v141, s50, v139
	s_cselect_b32 s25, s9, s48
	s_cselect_b32 s24, s46, s47
	s_add_i32 s52, 0, 0x14000
	ds_read_b128 v[142:145], v141
	ds_read_b128 v[146:149], v141 offset:1024
	ds_read_b128 v[150:153], v141 offset:2048
	ds_read_b128 v[154:157], v141 offset:3072
	v_add_u32_e32 v141, s52, v139
	ds_read_b128 v[158:161], v141
	ds_read_b128 v[162:165], v141 offset:1024
	ds_read_b128 v[166:169], v141 offset:2048
	ds_read_b128 v[170:173], v141 offset:3072
	v_lshl_add_u64 v[194:195], s[22:23], 0, v[136:137]
	s_add_i32 m0, s21, 0xc000
	ds_read_b128 v[174:177], v140
	ds_read_b128 v[178:181], v140 offset:1024
	ds_read_b128 v[182:185], v140 offset:2048
	ds_read_b128 v[186:189], v140 offset:3072
	ds_read_b128 v[190:193], v140 offset:4096
	ds_read_b128 v[208:211], v140 offset:5120
	ds_read_b128 v[212:215], v140 offset:6144
	ds_read_b128 v[216:219], v140 offset:7168
	global_load_lds_dwordx4 v[194:195], off
	v_lshl_add_u64 v[194:195], s[22:23], 0, v[134:135]
	s_add_i32 m0, s21, 0xe000
	s_nop 0
	global_load_lds_dwordx4 v[194:195], off
	s_waitcnt vmcnt(8)
	s_waitcnt lgkmcnt(0)
	v_mfma_f32_16x16x32_f16 v[128:131], v[142:145], v[174:177], v[128:131]
	v_mfma_f32_16x16x32_f16 v[120:123], v[150:153], v[174:177], v[120:123]
	v_mfma_f32_16x16x32_f16 v[112:115], v[142:145], v[182:185], v[112:115]
	v_mfma_f32_16x16x32_f16 v[104:107], v[150:153], v[182:185], v[104:107]
	v_mfma_f32_16x16x32_f16 v[96:99], v[142:145], v[190:193], v[96:99]
	v_mfma_f32_16x16x32_f16 v[88:91], v[150:153], v[190:193], v[88:91]
	v_mfma_f32_16x16x32_f16 v[80:83], v[142:145], v[212:215], v[80:83]
	v_mfma_f32_16x16x32_f16 v[72:75], v[150:153], v[212:215], v[72:75]
	s_barrier
	s_setprio 1
	v_mfma_f32_16x16x32_f16 v[128:131], v[146:149], v[178:181], v[128:131]
	v_mfma_f32_16x16x32_f16 v[120:123], v[154:157], v[178:181], v[120:123]
	v_mfma_f32_16x16x32_f16 v[112:115], v[146:149], v[186:189], v[112:115]
	v_mfma_f32_16x16x32_f16 v[104:107], v[154:157], v[186:189], v[104:107]
	v_mfma_f32_16x16x32_f16 v[96:99], v[146:149], v[208:211], v[96:99]
	v_mfma_f32_16x16x32_f16 v[88:91], v[154:157], v[208:211], v[88:91]
	v_mfma_f32_16x16x32_f16 v[80:83], v[146:149], v[216:219], v[80:83]
	v_mfma_f32_16x16x32_f16 v[72:75], v[154:157], v[216:219], v[72:75]
	v_mfma_f32_16x16x32_f16 v[124:127], v[158:161], v[174:177], v[124:127]
	v_mfma_f32_16x16x32_f16 v[116:119], v[166:169], v[174:177], v[116:119]
	v_mfma_f32_16x16x32_f16 v[108:111], v[158:161], v[182:185], v[108:111]
	v_mfma_f32_16x16x32_f16 v[100:103], v[166:169], v[182:185], v[100:103]
	v_mfma_f32_16x16x32_f16 v[92:95], v[158:161], v[190:193], v[92:95]
	v_mfma_f32_16x16x32_f16 v[84:87], v[166:169], v[190:193], v[84:87]
	v_mfma_f32_16x16x32_f16 v[76:79], v[158:161], v[212:215], v[76:79]
	v_mfma_f32_16x16x32_f16 v[68:71], v[166:169], v[212:215], v[68:71]
	v_mfma_f32_16x16x32_f16 v[124:127], v[162:165], v[178:181], v[124:127]
	v_mfma_f32_16x16x32_f16 v[116:119], v[170:173], v[178:181], v[116:119]
	v_mfma_f32_16x16x32_f16 v[108:111], v[162:165], v[186:189], v[108:111]
	v_mfma_f32_16x16x32_f16 v[100:103], v[170:173], v[186:189], v[100:103]
	v_mfma_f32_16x16x32_f16 v[92:95], v[162:165], v[208:211], v[92:95]
	v_mfma_f32_16x16x32_f16 v[84:87], v[170:173], v[208:211], v[84:87]
	v_mfma_f32_16x16x32_f16 v[76:79], v[162:165], v[216:219], v[76:79]
	v_mfma_f32_16x16x32_f16 v[68:71], v[170:173], v[216:219], v[68:71]
	s_setprio 0
	s_barrier
	s_add_i32 s50, s50, s36
	v_lshl_add_u64 v[194:195], s[24:25], 0, v[0:1]
	s_mov_b32 m0, s50
	ds_read_b128 v[174:177], v140 offset:16384
	ds_read_b128 v[178:181], v140 offset:17408
	ds_read_b128 v[182:185], v140 offset:18432
	ds_read_b128 v[186:189], v140 offset:19456
	ds_read_b128 v[190:193], v140 offset:20480
	ds_read_b128 v[208:211], v140 offset:21504
	ds_read_b128 v[212:215], v140 offset:22528
	ds_read_b128 v[216:219], v140 offset:23552
	global_load_lds_dwordx4 v[194:195], off
	s_add_i32 m0, s50, 0x2000
	s_add_u32 s50, s24, 0x20000
	v_lshl_add_u64 v[220:221], s[24:25], 0, v[132:133]
	s_addc_u32 s51, s25, 0
	s_add_i32 s52, s52, s36
	global_load_lds_dwordx4 v[220:221], off
	v_lshl_add_u64 v[222:223], s[50:51], 0, v[0:1]
	s_mov_b32 m0, s52
	v_lshl_add_u64 v[224:225], s[26:27], 0, v[132:133]
	global_load_lds_dwordx4 v[222:223], off
	v_lshl_add_u64 v[222:223], s[50:51], 0, v[132:133]
	s_add_i32 m0, s52, 0x2000
	s_nop 0
	global_load_lds_dwordx4 v[222:223], off
	v_lshl_add_u64 v[222:223], s[26:27], 0, v[0:1]
	s_mov_b32 m0, s21
	s_nop 0
	global_load_lds_dwordx4 v[222:223], off
	s_mov_b32 m0, s37
	s_nop 0
	global_load_lds_dwordx4 v[224:225], off
	s_waitcnt vmcnt(8)
	s_waitcnt lgkmcnt(0)
	v_mfma_f32_16x16x32_f16 v[64:67], v[142:145], v[174:177], v[64:67]
	v_mfma_f32_16x16x32_f16 v[56:59], v[150:153], v[174:177], v[56:59]
	v_mfma_f32_16x16x32_f16 v[48:51], v[142:145], v[182:185], v[48:51]
	v_mfma_f32_16x16x32_f16 v[40:43], v[150:153], v[182:185], v[40:43]
	v_mfma_f32_16x16x32_f16 v[32:35], v[142:145], v[190:193], v[32:35]
	v_mfma_f32_16x16x32_f16 v[24:27], v[150:153], v[190:193], v[24:27]
	v_mfma_f32_16x16x32_f16 v[16:19], v[142:145], v[212:215], v[16:19]
	v_mfma_f32_16x16x32_f16 v[8:11], v[150:153], v[212:215], v[8:11]
	s_barrier
; #define PG8_STAGE(bufoff, gbase, voff) do { _Pragma("unroll") for (int _i = 0; _i < 2; ++_i) \
;         __builtin_amdgcn_global_load_lds((const unsigned*)((const char*)(gbase) + (voff)[_i]), (LAS unsigned*)(lds + (bufoff) + ldsw + _i * 8192), 16, 0, 0); } while (0)
; #define PG8_LDA(dst, b, h) do { _Pragma("unroll") for (int m = 0; m < 4; ++m) _Pragma("unroll") for (int k = 0; k < 2; ++k) dst[m][k] = *(const LAS bf16x8*)(lds + PG8_SA(b, h) + aoff + m * 2048 + k * 1024); } while (0)
; #define PG8_LDB(dst, b, h) do { _Pragma("unroll") for (int n = 0; n < 2; ++n) _Pragma("unroll") for (int k = 0; k < 2; ++k) dst[n][k] = *(const LAS bf16x8*)(lds + PG8_SB(b, h) + boff + n * 2048 + k * 1024); } while (0)
; #define PG8_WAIT_V(n) asm volatile("s_waitcnt vmcnt(" #n ")" ::: "memory")
; #define PG8_WAIT_L(n) asm volatile("s_waitcnt lgkmcnt(" #n ")" ::: "memory")
; #define PG8_BAR __builtin_amdgcn_s_barrier()
; #define PG8_SCHED __builtin_amdgcn_sched_barrier(0)
; template <class Epi, class Sched, bool FUSED = false, bool APERM = false>
; __device__ __forceinline__ void gemm_phase(int wid_s, LAS unsigned char* lds, const Gemm g, const Sched& S, const Epi& E) {
;     ...
;             PG8_WAIT_V(8); PG8_WAIT_L(0); PG8_BAR; PG8_MMA(1, 0, At, B0); PG8_MMA(1, 1, At, B1); PG8_BAR; PG8_SCHED;
;             PG8_LDB(B0, 1, 0); PG8_LDB(B1, 1, 1); PG8_SCHED; PG8_LDA(At, 1, 0); PG8_STAGE(PG8_SA(0, 1), a2 + hstep, voffA);
;             PG8_WAIT_V(8); PG8_WAIT_L(0); PG8_BAR; PG8_MMA(0, 0, At, B0); PG8_MMA(0, 1, At, B1); PG8_BAR; PG8_SCHED;
	s_setprio 1
	v_mfma_f32_16x16x32_f16 v[64:67], v[146:149], v[178:181], v[64:67]
	v_mfma_f32_16x16x32_f16 v[56:59], v[154:157], v[178:181], v[56:59]
	v_mfma_f32_16x16x32_f16 v[48:51], v[146:149], v[186:189], v[48:51]
	v_mfma_f32_16x16x32_f16 v[40:43], v[154:157], v[186:189], v[40:43]
	v_mfma_f32_16x16x32_f16 v[32:35], v[146:149], v[208:211], v[32:35]
	v_mfma_f32_16x16x32_f16 v[24:27], v[154:157], v[208:211], v[24:27]
	v_mfma_f32_16x16x32_f16 v[16:19], v[146:149], v[216:219], v[16:19]
	v_mfma_f32_16x16x32_f16 v[8:11], v[154:157], v[216:219], v[8:11]
	v_mfma_f32_16x16x32_f16 v[60:63], v[158:161], v[174:177], v[60:63]
	v_mfma_f32_16x16x32_f16 v[52:55], v[166:169], v[174:177], v[52:55]
	v_mfma_f32_16x16x32_f16 v[44:47], v[158:161], v[182:185], v[44:47]
	v_mfma_f32_16x16x32_f16 v[36:39], v[166:169], v[182:185], v[36:39]
	v_mfma_f32_16x16x32_f16 v[28:31], v[158:161], v[190:193], v[28:31]
	v_mfma_f32_16x16x32_f16 v[20:23], v[166:169], v[190:193], v[20:23]
	v_mfma_f32_16x16x32_f16 v[12:15], v[158:161], v[212:215], v[12:15]
	v_mfma_f32_16x16x32_f16 v[4:7], v[166:169], v[212:215], v[4:7]
	v_mfma_f32_16x16x32_f16 v[60:63], v[162:165], v[178:181], v[60:63]
	v_mfma_f32_16x16x32_f16 v[52:55], v[170:173], v[178:181], v[52:55]
	v_mfma_f32_16x16x32_f16 v[44:47], v[162:165], v[186:189], v[44:47]
	v_mfma_f32_16x16x32_f16 v[36:39], v[170:173], v[186:189], v[36:39]
	v_mfma_f32_16x16x32_f16 v[28:31], v[162:165], v[208:211], v[28:31]
	v_mfma_f32_16x16x32_f16 v[20:23], v[170:173], v[208:211], v[20:23]
	v_mfma_f32_16x16x32_f16 v[12:15], v[162:165], v[216:219], v[12:15]
	v_mfma_f32_16x16x32_f16 v[4:7], v[170:173], v[216:219], v[4:7]
	s_setprio 0
	s_barrier
	s_add_i32 s50, 0, 0x18000
	v_add_u32_e32 v141, s50, v139
	s_add_i32 s51, 0, 0x1c000
	ds_read_b128 v[142:145], v141
	ds_read_b128 v[146:149], v141 offset:1024
	ds_read_b128 v[150:153], v141 offset:2048
	ds_read_b128 v[154:157], v141 offset:3072
	v_add_u32_e32 v141, s51, v139
	ds_read_b128 v[158:161], v141
	ds_read_b128 v[162:165], v141 offset:1024
	ds_read_b128 v[166:169], v141 offset:2048
	ds_read_b128 v[170:173], v141 offset:3072
	s_add_u32 s26, s26, 0x20000
	s_addc_u32 s27, s27, 0
	s_mov_b32 m0, s38
	v_lshl_add_u64 v[226:227], s[26:27], 0, v[0:1]
	ds_read_b128 v[174:177], v140 offset:32768
	ds_read_b128 v[178:181], v140 offset:33792
	ds_read_b128 v[182:185], v140 offset:34816
	ds_read_b128 v[186:189], v140 offset:35840
	ds_read_b128 v[190:193], v140 offset:36864
	ds_read_b128 v[208:211], v140 offset:37888
	ds_read_b128 v[212:215], v140 offset:38912
	ds_read_b128 v[216:219], v140 offset:39936
	global_load_lds_dwordx4 v[226:227], off
	v_lshl_add_u64 v[226:227], s[26:27], 0, v[132:133]
	s_mov_b32 m0, s39
	s_nop 0
	global_load_lds_dwordx4 v[226:227], off
	s_waitcnt vmcnt(8)
	s_waitcnt lgkmcnt(0)
	v_mfma_f32_16x16x32_f16 v[128:131], v[142:145], v[174:177], v[128:131]
	v_mfma_f32_16x16x32_f16 v[120:123], v[150:153], v[174:177], v[120:123]
	v_mfma_f32_16x16x32_f16 v[112:115], v[142:145], v[182:185], v[112:115]
	v_mfma_f32_16x16x32_f16 v[104:107], v[150:153], v[182:185], v[104:107]
	v_mfma_f32_16x16x32_f16 v[96:99], v[142:145], v[190:193], v[96:99]
	v_mfma_f32_16x16x32_f16 v[88:91], v[150:153], v[190:193], v[88:91]
	v_mfma_f32_16x16x32_f16 v[80:83], v[142:145], v[212:215], v[80:83]
	v_mfma_f32_16x16x32_f16 v[72:75], v[150:153], v[212:215], v[72:75]
	s_barrier
	s_setprio 1
	v_mfma_f32_16x16x32_f16 v[128:131], v[146:149], v[178:181], v[128:131]
	v_mfma_f32_16x16x32_f16 v[120:123], v[154:157], v[178:181], v[120:123]
	v_mfma_f32_16x16x32_f16 v[112:115], v[146:149], v[186:189], v[112:115]
	v_mfma_f32_16x16x32_f16 v[104:107], v[154:157], v[186:189], v[104:107]
	v_mfma_f32_16x16x32_f16 v[96:99], v[146:149], v[208:211], v[96:99]
	v_mfma_f32_16x16x32_f16 v[88:91], v[154:157], v[208:211], v[88:91]
	v_mfma_f32_16x16x32_f16 v[80:83], v[146:149], v[216:219], v[80:83]
	v_mfma_f32_16x16x32_f16 v[72:75], v[154:157], v[216:219], v[72:75]
	v_mfma_f32_16x16x32_f16 v[124:127], v[158:161], v[174:177], v[124:127]
	v_mfma_f32_16x16x32_f16 v[116:119], v[166:169], v[174:177], v[116:119]
	v_mfma_f32_16x16x32_f16 v[108:111], v[158:161], v[182:185], v[108:111]
	v_mfma_f32_16x16x32_f16 v[100:103], v[166:169], v[182:185], v[100:103]
	v_mfma_f32_16x16x32_f16 v[92:95], v[158:161], v[190:193], v[92:95]
	v_mfma_f32_16x16x32_f16 v[84:87], v[166:169], v[190:193], v[84:87]
	v_mfma_f32_16x16x32_f16 v[76:79], v[158:161], v[212:215], v[76:79]
	v_mfma_f32_16x16x32_f16 v[68:71], v[166:169], v[212:215], v[68:71]
	v_mfma_f32_16x16x32_f16 v[124:127], v[162:165], v[178:181], v[124:127]
	v_mfma_f32_16x16x32_f16 v[116:119], v[170:173], v[178:181], v[116:119]
	v_mfma_f32_16x16x32_f16 v[108:111], v[162:165], v[186:189], v[108:111]
	v_mfma_f32_16x16x32_f16 v[100:103], v[170:173], v[186:189], v[100:103]
	v_mfma_f32_16x16x32_f16 v[92:95], v[162:165], v[208:211], v[92:95]
	v_mfma_f32_16x16x32_f16 v[84:87], v[170:173], v[208:211], v[84:87]
	v_mfma_f32_16x16x32_f16 v[76:79], v[162:165], v[216:219], v[76:79]
	v_mfma_f32_16x16x32_f16 v[68:71], v[170:173], v[216:219], v[68:71]
	s_setprio 0
	s_barrier
; #define PG8_STAGE(bufoff, gbase, voff) do { _Pragma("unroll") for (int _i = 0; _i < 2; ++_i) \
;         __builtin_amdgcn_global_load_lds((const unsigned*)((const char*)(gbase) + (voff)[_i]), (LAS unsigned*)(lds + (bufoff) + ldsw + _i * 8192), 16, 0, 0); } while (0)
; #define PG8_LDA(dst, b, h) do { _Pragma("unroll") for (int m = 0; m < 4; ++m) _Pragma("unroll") for (int k = 0; k < 2; ++k) dst[m][k] = *(const LAS bf16x8*)(lds + PG8_SA(b, h) + aoff + m * 2048 + k * 1024); } while (0)
; #define PG8_WAIT_V(n) asm volatile("s_waitcnt vmcnt(" #n ")" ::: "memory")
; #define PG8_WAIT_L(n) asm volatile("s_waitcnt lgkmcnt(" #n ")" ::: "memory")
; #define PG8_BAR __builtin_amdgcn_s_barrier()
; #define PG8_SCHED __builtin_amdgcn_sched_barrier(0)
; template <class Epi, class Sched, bool FUSED = false, bool APERM = false>
; __device__ __forceinline__ void gemm_phase(int wid_s, LAS unsigned char* lds, const Gemm g, const Sched& S, const Epi& E) {
;     ...
;             PG8_LDA(At, 1, 1); PG8_STAGE(PG8_SB(1, 0), b3, voffB); PG8_STAGE(PG8_SB(1, 1), b3 + hstep, voffB); PG8_STAGE(PG8_SA(1, 0), a3, voffA);
;             PG8_WAIT_V(8); PG8_WAIT_L(0); PG8_BAR; PG8_MMA(1, 0, At, B0); PG8_MMA(1, 1, At, B1); PG8_BAR; PG8_SCHED;
;         }
;         if (wr == 0) PG8_BAR;
	s_add_i32 s26, s50, s36
	v_lshl_add_u64 v[194:195], v[194:195], 0, s[12:13]
	s_mov_b32 m0, s26
	ds_read_b128 v[174:177], v140 offset:49152
	ds_read_b128 v[178:181], v140 offset:50176
	ds_read_b128 v[182:185], v140 offset:51200
	ds_read_b128 v[186:189], v140 offset:52224
	ds_read_b128 v[190:193], v140 offset:53248
	ds_read_b128 v[208:211], v140 offset:54272
	ds_read_b128 v[212:215], v140 offset:55296
	ds_read_b128 v[216:219], v140 offset:56320
	global_load_lds_dwordx4 v[194:195], off
	s_add_i32 m0, s26, 0x2000
	s_add_u32 s24, s24, 0x20080
	v_lshl_add_u64 v[194:195], v[220:221], 0, s[12:13]
	s_addc_u32 s25, s25, 0
	s_add_i32 s26, s51, s36
	global_load_lds_dwordx4 v[194:195], off
	v_lshl_add_u64 v[194:195], s[24:25], 0, v[0:1]
	s_mov_b32 m0, s26
	s_nop 0
	global_load_lds_dwordx4 v[194:195], off
	v_lshl_add_u64 v[194:195], s[24:25], 0, v[132:133]
	s_add_i32 m0, s26, 0x2000
	s_nop 0
	global_load_lds_dwordx4 v[194:195], off
	v_lshl_add_u64 v[194:195], v[222:223], 0, s[12:13]
	s_mov_b32 m0, s41
	s_nop 0
	global_load_lds_dwordx4 v[194:195], off
	v_lshl_add_u64 v[194:195], v[224:225], 0, s[12:13]
	s_mov_b32 m0, s42
	s_nop 0
	global_load_lds_dwordx4 v[194:195], off
	s_waitcnt vmcnt(8)
	s_waitcnt lgkmcnt(0)
	v_mfma_f32_16x16x32_f16 v[64:67], v[142:145], v[174:177], v[64:67]
	v_mfma_f32_16x16x32_f16 v[56:59], v[150:153], v[174:177], v[56:59]
	v_mfma_f32_16x16x32_f16 v[48:51], v[142:145], v[182:185], v[48:51]
	v_mfma_f32_16x16x32_f16 v[40:43], v[150:153], v[182:185], v[40:43]
	v_mfma_f32_16x16x32_f16 v[32:35], v[142:145], v[190:193], v[32:35]
	v_mfma_f32_16x16x32_f16 v[24:27], v[150:153], v[190:193], v[24:27]
	v_mfma_f32_16x16x32_f16 v[16:19], v[142:145], v[212:215], v[16:19]
	v_mfma_f32_16x16x32_f16 v[8:11], v[150:153], v[212:215], v[8:11]
	s_barrier
	s_setprio 1
	v_mfma_f32_16x16x32_f16 v[64:67], v[146:149], v[178:181], v[64:67]
	v_mfma_f32_16x16x32_f16 v[56:59], v[154:157], v[178:181], v[56:59]
	v_mfma_f32_16x16x32_f16 v[48:51], v[146:149], v[186:189], v[48:51]
	v_mfma_f32_16x16x32_f16 v[40:43], v[154:157], v[186:189], v[40:43]
	v_mfma_f32_16x16x32_f16 v[32:35], v[146:149], v[208:211], v[32:35]
	v_mfma_f32_16x16x32_f16 v[24:27], v[154:157], v[208:211], v[24:27]
	v_mfma_f32_16x16x32_f16 v[16:19], v[146:149], v[216:219], v[16:19]
	v_mfma_f32_16x16x32_f16 v[8:11], v[154:157], v[216:219], v[8:11]
	v_mfma_f32_16x16x32_f16 v[60:63], v[158:161], v[174:177], v[60:63]
	v_mfma_f32_16x16x32_f16 v[52:55], v[166:169], v[174:177], v[52:55]
	v_mfma_f32_16x16x32_f16 v[44:47], v[158:161], v[182:185], v[44:47]
	v_mfma_f32_16x16x32_f16 v[36:39], v[166:169], v[182:185], v[36:39]
	v_mfma_f32_16x16x32_f16 v[28:31], v[158:161], v[190:193], v[28:31]
	v_mfma_f32_16x16x32_f16 v[20:23], v[166:169], v[190:193], v[20:23]
	v_mfma_f32_16x16x32_f16 v[12:15], v[158:161], v[212:215], v[12:15]
	v_mfma_f32_16x16x32_f16 v[4:7], v[166:169], v[212:215], v[4:7]
	v_mfma_f32_16x16x32_f16 v[60:63], v[162:165], v[178:181], v[60:63]
	v_mfma_f32_16x16x32_f16 v[52:55], v[170:173], v[178:181], v[52:55]
	v_mfma_f32_16x16x32_f16 v[44:47], v[162:165], v[186:189], v[44:47]
	v_mfma_f32_16x16x32_f16 v[36:39], v[170:173], v[186:189], v[36:39]
	v_mfma_f32_16x16x32_f16 v[28:31], v[162:165], v[208:211], v[28:31]
	v_mfma_f32_16x16x32_f16 v[20:23], v[170:173], v[208:211], v[20:23]
	v_mfma_f32_16x16x32_f16 v[12:15], v[162:165], v[216:219], v[12:15]
	v_mfma_f32_16x16x32_f16 v[4:7], v[170:173], v[216:219], v[4:7]
	s_setprio 0
	s_barrier
	s_add_i32 s49, s49, 2
	s_add_u32 s47, s47, 0x100
	s_addc_u32 s48, s48, 0
	s_add_u32 s22, s22, 0x100
	s_addc_u32 s23, s23, 0
	s_cmp_gt_u32 s49, 5
	s_cbranch_scc0 .LBB0_582
	s_and_b64 vcc, exec, s[6:7]
	s_cbranch_vccz .LBB0_585
	s_barrier
